# pool-window phase: trailing-window row loads issued four at a time (predicated) instead of one load per vmcnt(0)
# speedup vs baseline: 1.0063x; 1.0063x over previous
; __global__ void __launch_bounds__(512) mega_fwd(Params p) {
;     ...
;                     const int t = (int)(idx / 192), chk = (int)(idx % 192), g = chk / 48, w = 2 << g, s = t & (SEQ - 1);
;                     const int cnt = (s + 1 < w) ? (s + 1) : w;
;                     const bf16_t* hp = hbuf + (size_t)t * MIX + chk * 8;
;                     float sum[8], self[8];
; #pragma unroll
;                     for (int j = 0; j < 8; ++j) sum[j] = 0.f;
;                     for (int i = 0; i < cnt; ++i) { const u32x4 v = *(const u32x4*)(hp - (size_t)i * MIX);
;                         const float e[8] = {__builtin_bit_cast(float, v.x << 16), __builtin_bit_cast(float, v.x & 0xffff0000u), __builtin_bit_cast(float, v.y << 16), __builtin_bit_cast(float, v.y & 0xffff0000u),
;                                             __builtin_bit_cast(float, v.z << 16), __builtin_bit_cast(float, v.z & 0xffff0000u), __builtin_bit_cast(float, v.w << 16), __builtin_bit_cast(float, v.w & 0xffff0000u)};
; #pragma unroll
;                         for (int j = 0; j < 8; ++j) { sum[j] += e[j]; if (i == 0) self[j] = e[j]; } }
.LBB0_359:
	s_mov_b32 s4, 0xaaaaaaab
	v_mul_hi_u32 v8, v2, s4
	v_lshrrev_b32_e32 v22, 7, v8
	s_movk_i32 s4, 0xc0
	v_mul_lo_u32 v0, v22, s4
	v_sub_u32_e32 v9, v2, v0
	v_mul_lo_u32 v0, v22, s16
	v_lshl_add_u64 v[4:5], v[0:1], 1, s[12:13]
	v_lshlrev_b32_e32 v6, 4, v9
	v_mov_b32_e32 v7, v1
	v_lshl_add_u64 v[4:5], v[4:5], 0, v[6:7]
	global_load_dwordx4 v[4:7], v[4:5], off
	v_bfe_u32 v8, v8, 7, 14
	v_add_u32_e32 v10, 1, v8
	v_cmp_ne_u32_e32 vcc, 0, v8
	v_mul_lo_u16_e32 v8, 0xab, v9
	v_lshrrev_b16_e32 v8, 13, v8
	v_lshlrev_b32_e64 v8, v8, 2
	v_lshlrev_b32_e32 v11, 3, v9
	v_min_u32_e32 v24, v8, v10
	v_lshlrev_b32_e32 v10, 1, v11
	s_waitcnt vmcnt(0)
	v_lshlrev_b32_e32 v14, 16, v4
	v_and_b32_e32 v15, 0xffff0000, v4
	v_lshlrev_b32_e32 v12, 16, v5
	v_and_b32_e32 v13, 0xffff0000, v5
	v_lshlrev_b32_e32 v8, 16, v6
	v_and_b32_e32 v9, 0xffff0000, v6
	v_lshlrev_b32_e32 v4, 16, v7
	v_and_b32_e32 v5, 0xffff0000, v7
	v_pk_add_f32 v[6:7], v[4:5], 0 op_sel_hi:[1,0]
	v_pk_add_f32 v[18:19], v[12:13], 0 op_sel_hi:[1,0]
	v_pk_add_f32 v[16:17], v[8:9], 0 op_sel_hi:[1,0]
	v_pk_add_f32 v[20:21], v[14:15], 0 op_sel_hi:[1,0]
	s_and_saveexec_b64 s[4:5], vcc
	s_cbranch_execz .LBB0_358
	v_mov_b32_e32 v11, v1
	s_movk_i32 s6, 0xc00
	v_mad_u64_u32 v[22:23], s[6:7], v22, s6, v[10:11]
	v_sub_u32_e32 v25, 1, v24
	v_lshl_add_u64 v[22:23], s[14:15], 0, v[22:23]
	s_mov_b64 s[6:7], exec
	s_mov_b32 s8, 0xffffe800
	s_mov_b32 s9, -1
	v_mov_b32_e32 v26, 0
	v_mov_b32_e32 v27, 0
	v_mov_b32_e32 v28, 0
	v_mov_b32_e32 v29, 0
	v_mov_b32_e32 v32, 0
	v_mov_b32_e32 v33, 0
	v_mov_b32_e32 v34, 0
	v_mov_b32_e32 v35, 0
	v_mov_b32_e32 v36, 0
	v_mov_b32_e32 v37, 0
	v_mov_b32_e32 v38, 0
	v_mov_b32_e32 v39, 0
	v_mov_b32_e32 v40, 0
	v_mov_b32_e32 v41, 0
	v_mov_b32_e32 v42, 0
	v_mov_b32_e32 v43, 0
	v_lshl_add_u64 v[30:31], v[22:23], 0, s[8:9]
	v_cmp_lt_u32_e32 vcc, 1, v24
	s_and_b64 exec, s[6:7], vcc
	global_load_dwordx4 v[26:29], v[22:23], off
	v_cmp_lt_u32_e32 vcc, 2, v24
	s_and_b64 exec, s[6:7], vcc
	global_load_dwordx4 v[32:35], v[22:23], off offset:-3072
	v_cmp_lt_u32_e32 vcc, 3, v24
	s_and_b64 exec, s[6:7], vcc
	global_load_dwordx4 v[36:39], v[30:31], off
	v_cmp_lt_u32_e32 vcc, 4, v24
	s_and_b64 exec, s[6:7], vcc
	global_load_dwordx4 v[40:43], v[30:31], off offset:-3072
	s_mov_b64 exec, s[6:7]
	v_lshl_add_u64 v[22:23], v[30:31], 0, s[8:9]
	s_waitcnt vmcnt(0)
	v_lshlrev_b32_e32 v44, 16, v26
	v_and_b32_e32 v45, 0xffff0000, v26
	v_pk_add_f32 v[20:21], v[20:21], v[44:45]
	v_lshlrev_b32_e32 v46, 16, v27
	v_and_b32_e32 v47, 0xffff0000, v27
	v_pk_add_f32 v[18:19], v[18:19], v[46:47]
	v_lshlrev_b32_e32 v44, 16, v28
	v_and_b32_e32 v45, 0xffff0000, v28
	v_pk_add_f32 v[16:17], v[16:17], v[44:45]
	v_lshlrev_b32_e32 v46, 16, v29
	v_and_b32_e32 v47, 0xffff0000, v29
	v_pk_add_f32 v[6:7], v[6:7], v[46:47]
	v_lshlrev_b32_e32 v44, 16, v32
	v_and_b32_e32 v45, 0xffff0000, v32
	v_pk_add_f32 v[20:21], v[20:21], v[44:45]
	v_lshlrev_b32_e32 v46, 16, v33
	v_and_b32_e32 v47, 0xffff0000, v33
	v_pk_add_f32 v[18:19], v[18:19], v[46:47]
	v_lshlrev_b32_e32 v44, 16, v34
	v_and_b32_e32 v45, 0xffff0000, v34
	v_pk_add_f32 v[16:17], v[16:17], v[44:45]
	v_lshlrev_b32_e32 v46, 16, v35
	v_and_b32_e32 v47, 0xffff0000, v35
	v_pk_add_f32 v[6:7], v[6:7], v[46:47]
	v_lshlrev_b32_e32 v44, 16, v36
	v_and_b32_e32 v45, 0xffff0000, v36
	v_pk_add_f32 v[20:21], v[20:21], v[44:45]
	v_lshlrev_b32_e32 v46, 16, v37
	v_and_b32_e32 v47, 0xffff0000, v37
	v_pk_add_f32 v[18:19], v[18:19], v[46:47]
	v_lshlrev_b32_e32 v44, 16, v38
	v_and_b32_e32 v45, 0xffff0000, v38
	v_pk_add_f32 v[16:17], v[16:17], v[44:45]
	v_lshlrev_b32_e32 v46, 16, v39
	v_and_b32_e32 v47, 0xffff0000, v39
	v_pk_add_f32 v[6:7], v[6:7], v[46:47]
	v_lshlrev_b32_e32 v44, 16, v40
	v_and_b32_e32 v45, 0xffff0000, v40
	v_pk_add_f32 v[20:21], v[20:21], v[44:45]
	v_lshlrev_b32_e32 v46, 16, v41
	v_and_b32_e32 v47, 0xffff0000, v41
	v_pk_add_f32 v[18:19], v[18:19], v[46:47]
	v_lshlrev_b32_e32 v44, 16, v42
	v_and_b32_e32 v45, 0xffff0000, v42
	v_pk_add_f32 v[16:17], v[16:17], v[44:45]
	v_lshlrev_b32_e32 v46, 16, v43
	v_and_b32_e32 v47, 0xffff0000, v43
	v_pk_add_f32 v[6:7], v[6:7], v[46:47]
	v_cmp_lt_u32_e32 vcc, 5, v24
	s_cbranch_vccz .Lpw_done
	v_mov_b32_e32 v26, 0
	v_mov_b32_e32 v27, 0
	v_mov_b32_e32 v28, 0
	v_mov_b32_e32 v29, 0
	v_mov_b32_e32 v32, 0
	v_mov_b32_e32 v33, 0
	v_mov_b32_e32 v34, 0
	v_mov_b32_e32 v35, 0
	v_mov_b32_e32 v36, 0
	v_mov_b32_e32 v37, 0
	v_mov_b32_e32 v38, 0
	v_mov_b32_e32 v39, 0
	v_mov_b32_e32 v40, 0
	v_mov_b32_e32 v41, 0
	v_mov_b32_e32 v42, 0
	v_mov_b32_e32 v43, 0
	v_lshl_add_u64 v[30:31], v[22:23], 0, s[8:9]
	v_cmp_lt_u32_e32 vcc, 5, v24
	s_and_b64 exec, s[6:7], vcc
	global_load_dwordx4 v[26:29], v[22:23], off
	v_cmp_lt_u32_e32 vcc, 6, v24
	s_and_b64 exec, s[6:7], vcc
	global_load_dwordx4 v[32:35], v[22:23], off offset:-3072
	v_cmp_lt_u32_e32 vcc, 7, v24
	s_and_b64 exec, s[6:7], vcc
	global_load_dwordx4 v[36:39], v[30:31], off
	v_cmp_lt_u32_e32 vcc, 8, v24
	s_and_b64 exec, s[6:7], vcc
	global_load_dwordx4 v[40:43], v[30:31], off offset:-3072
	s_mov_b64 exec, s[6:7]
	v_lshl_add_u64 v[22:23], v[30:31], 0, s[8:9]
	s_waitcnt vmcnt(0)
	v_lshlrev_b32_e32 v44, 16, v26
	v_and_b32_e32 v45, 0xffff0000, v26
	v_pk_add_f32 v[20:21], v[20:21], v[44:45]
	v_lshlrev_b32_e32 v46, 16, v27
	v_and_b32_e32 v47, 0xffff0000, v27
	v_pk_add_f32 v[18:19], v[18:19], v[46:47]
	v_lshlrev_b32_e32 v44, 16, v28
	v_and_b32_e32 v45, 0xffff0000, v28
	v_pk_add_f32 v[16:17], v[16:17], v[44:45]
	v_lshlrev_b32_e32 v46, 16, v29
	v_and_b32_e32 v47, 0xffff0000, v29
	v_pk_add_f32 v[6:7], v[6:7], v[46:47]
	v_lshlrev_b32_e32 v44, 16, v32
	v_and_b32_e32 v45, 0xffff0000, v32
	v_pk_add_f32 v[20:21], v[20:21], v[44:45]
	v_lshlrev_b32_e32 v46, 16, v33
	v_and_b32_e32 v47, 0xffff0000, v33
	v_pk_add_f32 v[18:19], v[18:19], v[46:47]
	v_lshlrev_b32_e32 v44, 16, v34
	v_and_b32_e32 v45, 0xffff0000, v34
	v_pk_add_f32 v[16:17], v[16:17], v[44:45]
	v_lshlrev_b32_e32 v46, 16, v35
	v_and_b32_e32 v47, 0xffff0000, v35
	v_pk_add_f32 v[6:7], v[6:7], v[46:47]
	v_lshlrev_b32_e32 v44, 16, v36
	v_and_b32_e32 v45, 0xffff0000, v36
	v_pk_add_f32 v[20:21], v[20:21], v[44:45]
	v_lshlrev_b32_e32 v46, 16, v37
	v_and_b32_e32 v47, 0xffff0000, v37
	v_pk_add_f32 v[18:19], v[18:19], v[46:47]
	v_lshlrev_b32_e32 v44, 16, v38
	v_and_b32_e32 v45, 0xffff0000, v38
	v_pk_add_f32 v[16:17], v[16:17], v[44:45]
	v_lshlrev_b32_e32 v46, 16, v39
	v_and_b32_e32 v47, 0xffff0000, v39
	v_pk_add_f32 v[6:7], v[6:7], v[46:47]
	v_lshlrev_b32_e32 v44, 16, v40
	v_and_b32_e32 v45, 0xffff0000, v40
	v_pk_add_f32 v[20:21], v[20:21], v[44:45]
	v_lshlrev_b32_e32 v46, 16, v41
	v_and_b32_e32 v47, 0xffff0000, v41
	v_pk_add_f32 v[18:19], v[18:19], v[46:47]
	v_lshlrev_b32_e32 v44, 16, v42
	v_and_b32_e32 v45, 0xffff0000, v42
	v_pk_add_f32 v[16:17], v[16:17], v[44:45]
	v_lshlrev_b32_e32 v46, 16, v43
	v_and_b32_e32 v47, 0xffff0000, v43
	v_pk_add_f32 v[6:7], v[6:7], v[46:47]
	v_cmp_lt_u32_e32 vcc, 9, v24
	s_cbranch_vccz .Lpw_done
; __global__ void __launch_bounds__(512) mega_fwd(Params p) {
;     ...
;                     for (int i = 0; i < cnt; ++i) { const u32x4 v = *(const u32x4*)(hp - (size_t)i * MIX);
;                         const float e[8] = {__builtin_bit_cast(float, v.x << 16), __builtin_bit_cast(float, v.x & 0xffff0000u), __builtin_bit_cast(float, v.y << 16), __builtin_bit_cast(float, v.y & 0xffff0000u),
;                                             __builtin_bit_cast(float, v.z << 16), __builtin_bit_cast(float, v.z & 0xffff0000u), __builtin_bit_cast(float, v.w << 16), __builtin_bit_cast(float, v.w & 0xffff0000u)};
; #pragma unroll
;                         for (int j = 0; j < 8; ++j) { sum[j] += e[j]; if (i == 0) self[j] = e[j]; } }
	v_mov_b32_e32 v26, 0
	v_mov_b32_e32 v27, 0
	v_mov_b32_e32 v28, 0
	v_mov_b32_e32 v29, 0
	v_mov_b32_e32 v32, 0
	v_mov_b32_e32 v33, 0
	v_mov_b32_e32 v34, 0
	v_mov_b32_e32 v35, 0
	v_mov_b32_e32 v36, 0
	v_mov_b32_e32 v37, 0
	v_mov_b32_e32 v38, 0
	v_mov_b32_e32 v39, 0
	v_mov_b32_e32 v40, 0
	v_mov_b32_e32 v41, 0
	v_mov_b32_e32 v42, 0
	v_mov_b32_e32 v43, 0
	v_lshl_add_u64 v[30:31], v[22:23], 0, s[8:9]
	v_cmp_lt_u32_e32 vcc, 9, v24
	s_and_b64 exec, s[6:7], vcc
	global_load_dwordx4 v[26:29], v[22:23], off
	v_cmp_lt_u32_e32 vcc, 10, v24
	s_and_b64 exec, s[6:7], vcc
	global_load_dwordx4 v[32:35], v[22:23], off offset:-3072
	v_cmp_lt_u32_e32 vcc, 11, v24
	s_and_b64 exec, s[6:7], vcc
	global_load_dwordx4 v[36:39], v[30:31], off
	v_cmp_lt_u32_e32 vcc, 12, v24
	s_and_b64 exec, s[6:7], vcc
	global_load_dwordx4 v[40:43], v[30:31], off offset:-3072
	s_mov_b64 exec, s[6:7]
	v_lshl_add_u64 v[22:23], v[30:31], 0, s[8:9]
	s_waitcnt vmcnt(0)
	v_lshlrev_b32_e32 v44, 16, v26
	v_and_b32_e32 v45, 0xffff0000, v26
	v_pk_add_f32 v[20:21], v[20:21], v[44:45]
	v_lshlrev_b32_e32 v46, 16, v27
	v_and_b32_e32 v47, 0xffff0000, v27
	v_pk_add_f32 v[18:19], v[18:19], v[46:47]
	v_lshlrev_b32_e32 v44, 16, v28
	v_and_b32_e32 v45, 0xffff0000, v28
	v_pk_add_f32 v[16:17], v[16:17], v[44:45]
	v_lshlrev_b32_e32 v46, 16, v29
	v_and_b32_e32 v47, 0xffff0000, v29
	v_pk_add_f32 v[6:7], v[6:7], v[46:47]
	v_lshlrev_b32_e32 v44, 16, v32
	v_and_b32_e32 v45, 0xffff0000, v32
	v_pk_add_f32 v[20:21], v[20:21], v[44:45]
	v_lshlrev_b32_e32 v46, 16, v33
	v_and_b32_e32 v47, 0xffff0000, v33
	v_pk_add_f32 v[18:19], v[18:19], v[46:47]
	v_lshlrev_b32_e32 v44, 16, v34
	v_and_b32_e32 v45, 0xffff0000, v34
	v_pk_add_f32 v[16:17], v[16:17], v[44:45]
	v_lshlrev_b32_e32 v46, 16, v35
	v_and_b32_e32 v47, 0xffff0000, v35
	v_pk_add_f32 v[6:7], v[6:7], v[46:47]
	v_lshlrev_b32_e32 v44, 16, v36
	v_and_b32_e32 v45, 0xffff0000, v36
	v_pk_add_f32 v[20:21], v[20:21], v[44:45]
	v_lshlrev_b32_e32 v46, 16, v37
	v_and_b32_e32 v47, 0xffff0000, v37
	v_pk_add_f32 v[18:19], v[18:19], v[46:47]
	v_lshlrev_b32_e32 v44, 16, v38
	v_and_b32_e32 v45, 0xffff0000, v38
	v_pk_add_f32 v[16:17], v[16:17], v[44:45]
	v_lshlrev_b32_e32 v46, 16, v39
	v_and_b32_e32 v47, 0xffff0000, v39
	v_pk_add_f32 v[6:7], v[6:7], v[46:47]
	v_lshlrev_b32_e32 v44, 16, v40
	v_and_b32_e32 v45, 0xffff0000, v40
	v_pk_add_f32 v[20:21], v[20:21], v[44:45]
	v_lshlrev_b32_e32 v46, 16, v41
	v_and_b32_e32 v47, 0xffff0000, v41
	v_pk_add_f32 v[18:19], v[18:19], v[46:47]
	v_lshlrev_b32_e32 v44, 16, v42
	v_and_b32_e32 v45, 0xffff0000, v42
	v_pk_add_f32 v[16:17], v[16:17], v[44:45]
	v_lshlrev_b32_e32 v46, 16, v43
	v_and_b32_e32 v47, 0xffff0000, v43
	v_pk_add_f32 v[6:7], v[6:7], v[46:47]
	v_cmp_lt_u32_e32 vcc, 13, v24
	s_cbranch_vccz .Lpw_done
	v_mov_b32_e32 v26, 0
	v_mov_b32_e32 v27, 0
	v_mov_b32_e32 v28, 0
	v_mov_b32_e32 v29, 0
	v_mov_b32_e32 v32, 0
	v_mov_b32_e32 v33, 0
	v_mov_b32_e32 v34, 0
	v_mov_b32_e32 v35, 0
	v_mov_b32_e32 v36, 0
	v_mov_b32_e32 v37, 0
	v_mov_b32_e32 v38, 0
	v_mov_b32_e32 v39, 0
	v_mov_b32_e32 v40, 0
	v_mov_b32_e32 v41, 0
	v_mov_b32_e32 v42, 0
	v_mov_b32_e32 v43, 0
	v_lshl_add_u64 v[30:31], v[22:23], 0, s[8:9]
	v_cmp_lt_u32_e32 vcc, 13, v24
	s_and_b64 exec, s[6:7], vcc
	global_load_dwordx4 v[26:29], v[22:23], off
	v_cmp_lt_u32_e32 vcc, 14, v24
	s_and_b64 exec, s[6:7], vcc
	global_load_dwordx4 v[32:35], v[22:23], off offset:-3072
	v_cmp_lt_u32_e32 vcc, 15, v24
	s_and_b64 exec, s[6:7], vcc
	global_load_dwordx4 v[36:39], v[30:31], off
	v_cmp_lt_u32_e32 vcc, 16, v24
	s_and_b64 exec, s[6:7], vcc
	global_load_dwordx4 v[40:43], v[30:31], off offset:-3072
	s_mov_b64 exec, s[6:7]
	v_lshl_add_u64 v[22:23], v[30:31], 0, s[8:9]
	s_waitcnt vmcnt(0)
	v_lshlrev_b32_e32 v44, 16, v26
	v_and_b32_e32 v45, 0xffff0000, v26
	v_pk_add_f32 v[20:21], v[20:21], v[44:45]
	v_lshlrev_b32_e32 v46, 16, v27
	v_and_b32_e32 v47, 0xffff0000, v27
	v_pk_add_f32 v[18:19], v[18:19], v[46:47]
	v_lshlrev_b32_e32 v44, 16, v28
	v_and_b32_e32 v45, 0xffff0000, v28
	v_pk_add_f32 v[16:17], v[16:17], v[44:45]
	v_lshlrev_b32_e32 v46, 16, v29
	v_and_b32_e32 v47, 0xffff0000, v29
	v_pk_add_f32 v[6:7], v[6:7], v[46:47]
	v_lshlrev_b32_e32 v44, 16, v32
	v_and_b32_e32 v45, 0xffff0000, v32
	v_pk_add_f32 v[20:21], v[20:21], v[44:45]
	v_lshlrev_b32_e32 v46, 16, v33
	v_and_b32_e32 v47, 0xffff0000, v33
	v_pk_add_f32 v[18:19], v[18:19], v[46:47]
	v_lshlrev_b32_e32 v44, 16, v34
	v_and_b32_e32 v45, 0xffff0000, v34
	v_pk_add_f32 v[16:17], v[16:17], v[44:45]
	v_lshlrev_b32_e32 v46, 16, v35
	v_and_b32_e32 v47, 0xffff0000, v35
	v_pk_add_f32 v[6:7], v[6:7], v[46:47]
	v_lshlrev_b32_e32 v44, 16, v36
	v_and_b32_e32 v45, 0xffff0000, v36
	v_pk_add_f32 v[20:21], v[20:21], v[44:45]
	v_lshlrev_b32_e32 v46, 16, v37
	v_and_b32_e32 v47, 0xffff0000, v37
	v_pk_add_f32 v[18:19], v[18:19], v[46:47]
	v_lshlrev_b32_e32 v44, 16, v38
	v_and_b32_e32 v45, 0xffff0000, v38
	v_pk_add_f32 v[16:17], v[16:17], v[44:45]
	v_lshlrev_b32_e32 v46, 16, v39
	v_and_b32_e32 v47, 0xffff0000, v39
	v_pk_add_f32 v[6:7], v[6:7], v[46:47]
	v_lshlrev_b32_e32 v44, 16, v40
	v_and_b32_e32 v45, 0xffff0000, v40
	v_pk_add_f32 v[20:21], v[20:21], v[44:45]
	v_lshlrev_b32_e32 v46, 16, v41
	v_and_b32_e32 v47, 0xffff0000, v41
	v_pk_add_f32 v[18:19], v[18:19], v[46:47]
	v_lshlrev_b32_e32 v44, 16, v42
	v_and_b32_e32 v45, 0xffff0000, v42
	v_pk_add_f32 v[16:17], v[16:17], v[44:45]
	v_lshlrev_b32_e32 v46, 16, v43
	v_and_b32_e32 v47, 0xffff0000, v43
	v_pk_add_f32 v[6:7], v[6:7], v[46:47]
.Lpw_done:
	s_branch .LBB0_358
